# baseline (speedup 1.0000x reference)
; __device__ __forceinline__ int opaque_tid(int wave_s) { int l; asm volatile("v_mbcnt_lo_u32_b32 %0, -1, 0\n\tv_mbcnt_hi_u32_b32 %0, -1, %0" : "=v"(l)); return (wave_s << 6) | l; }
; #define LAS __attribute__((address_space(3)))
; __device__ __forceinline__ unsigned pk2(float lo, float hi) { return pg8::cvt_pk_bf16(lo, hi); }
; template <int NCH, class RB, class EP>
; __device__ __forceinline__ void tail_gemm(const bf16* A16, const bf16* Bt, int K, int ngroups, int vcu, int G, LAS unsigned char* lds, int wave, RB rb, EP ep) {
;     const int tid = opaque_tid(wave), lane = tid & 63, r = lane & 15, q = lane >> 4;
;     LAS float* red = (LAS float*)lds;
;     const int kw = K >> 3;
; #pragma unroll 1
;     for (int g = vcu; g < ngroups; g += G) {
;         f32x4 acc[NCH];
; #pragma unroll
;         for (int c = 0; c < NCH; ++c) acc[c] = (f32x4){0.f, 0.f, 0.f, 0.f};
;         const bf16* ap = A16 + (size_t)r * K + wave * kw + 8 * q;
; #pragma unroll 2
;         for (int k = 0; k < kw; k += 32) {
;             const bf16x8 av = *(const bf16x8*)(ap + k);
; #pragma unroll
;             for (int c = 0; c < NCH; ++c) { const bf16x8 bv = *(const bf16x8*)(Bt + (size_t)(rb(g, c) + r) * K + wave * kw + 8 * q + k);
;                 acc[c] = __builtin_amdgcn_mfma_f32_16x16x32_bf16(av, bv, acc[c], 0, 0, 0); }
; __global__ void __launch_bounds__(NTHR, 2) mk_fwd(Args a_byval) {
;     ...
;                 { bf16* QR = (bf16*)(ws + WS_QRAW);
;                   for (int rep = 0; rep < DUP_TAIL; ++rep)
;                   tail_gemm<1>((const bf16*)(ws + WS_CQN) + (size_t)8192 * QL, (const bf16*)(wl + OFF_WUQ), QL, 1536 / 16, vcu, G, lds, wave0,
;                       [](int g, int) { return g * 16; }, [=](int g, int r, int c, const float* v) { QR[(size_t)(8192 + r) * 1536 + g * 16 + c] = (bf16)(pk2(v[0], 0.f) & 0xffffu); }); }
.LBB0_414:
	v_readlane_b32 s11, v255, 7
	s_cmpk_lt_i32 s11, 0xc0
	v_mbcnt_lo_u32_b32 v4, -1, 0
	v_mbcnt_hi_u32_b32 v4, -1, v4
	s_cbranch_scc1 .LBB0_419
	v_readlane_b32 s24, v253, 25
	v_readlane_b32 s25, v253, 26
	s_lshl_b64 s[20:21], s[24:25], 1
	s_add_u32 s22, s43, s20
	v_readlane_b32 s0, v255, 9
	s_addc_u32 s23, s0, s21
	v_and_b32_e32 v6, 15, v4
	s_add_u32 s20, s16, s20
	v_or_b32_e32 v5, s24, v4
	s_movk_i32 s0, 0x100
	s_addc_u32 s21, s17, s21
	v_lshlrev_b32_e32 v148, 10, v6
	v_cmp_gt_i32_e32 vcc, s0, v5
	s_waitcnt vmcnt(0)
	v_lshl_add_u32 v8, v5, 2, 0
	v_ashrrev_i32_e32 v5, 4, v5
	v_readlane_b32 s0, v255, 10
	v_lshl_add_u64 v[0:1], s[20:21], 0, v[148:149]
	v_lshrrev_b32_e32 v9, 1, v4
	v_and_b32_e32 v148, 48, v4
	v_lshlrev_b32_e32 v7, 4, v4
	v_bfi_b32 v4, -4, v5, v4
	v_readlane_b32 s1, v255, 11
	v_lshl_add_u64 v[0:1], v[0:1], 0, v[148:149]
	s_mov_b64 s[20:21], 0x20410000
	v_add_u32_e32 v10, 0x2000, v4
	v_mov_b64_e32 v[4:5], s[0:1]
	s_movk_i32 s0, 0xc00
	v_lshl_add_u64 v[0:1], v[0:1], 0, s[20:21]
	v_lshl_add_u64 v[2:3], s[22:23], 0, v[148:149]
	v_and_b32_e32 v7, 0x3f0, v7
	v_mad_i64_i32 v[4:5], s[20:21], v10, s0, v[4:5]
	v_and_b32_e32 v148, 30, v9
	v_add_u32_e32 v7, s87, v7
	v_lshl_add_u64 v[4:5], v[4:5], 0, v[148:149]
	s_add_i32 s7, s11, 0xffffff40
	s_lshl_b32 s22, s7, 4
	s_movk_i32 s5, 0x400
	s_branch .LBB0_417
.LBB0_416:
	s_or_b64 exec, exec, s[24:25]
	s_addk_i32 s7, 0x40
	s_add_i32 s22, s22, s5
	s_cmpk_lt_i32 s7, 0x60
	s_barrier
	s_cbranch_scc0 .LBB0_419

; __device__ __forceinline__ int opaque_tid(int wave_s) { int l; asm volatile("v_mbcnt_lo_u32_b32 %0, -1, 0\n\tv_mbcnt_hi_u32_b32 %0, -1, %0" : "=v"(l)); return (wave_s << 6) | l; }
; #define LAS __attribute__((address_space(3)))
; __device__ __forceinline__ unsigned pk2(float lo, float hi) { return pg8::cvt_pk_bf16(lo, hi); }
; template <int NCH, class RB, class EP>
; __device__ __forceinline__ void tail_gemm(const bf16* A16, const bf16* Bt, int K, int ngroups, int vcu, int G, LAS unsigned char* lds, int wave, RB rb, EP ep) {
;     const int tid = opaque_tid(wave), lane = tid & 63, r = lane & 15, q = lane >> 4;
;     LAS float* red = (LAS float*)lds;
;     const int kw = K >> 3;
; #pragma unroll 1
;     for (int g = vcu; g < ngroups; g += G) {
;         f32x4 acc[NCH];
; #pragma unroll
;         for (int c = 0; c < NCH; ++c) acc[c] = (f32x4){0.f, 0.f, 0.f, 0.f};
;         const bf16* ap = A16 + (size_t)r * K + wave * kw + 8 * q;
; #pragma unroll 2
;         for (int k = 0; k < kw; k += 32) {
;             const bf16x8 av = *(const bf16x8*)(ap + k);
; #pragma unroll
;             for (int c = 0; c < NCH; ++c) { const bf16x8 bv = *(const bf16x8*)(Bt + (size_t)(rb(g, c) + r) * K + wave * kw + 8 * q + k);
;                 acc[c] = __builtin_amdgcn_mfma_f32_16x16x32_bf16(av, bv, acc[c], 0, 0, 0); }
; __global__ void __launch_bounds__(NTHR, 2) mk_fwd(Args a_byval) {
;     ...
;                 { bf16* KVR = (bf16*)(ws + WS_KVRAW);
;                   for (int rep = 0; rep < DUP_TAIL; ++rep)
;                   tail_gemm<1>((const bf16*)(ws + WS_CKVN) + (size_t)8192 * KVL, (const bf16*)(wl + OFF_WUKV), KVL, 2048 / 16, vcu, G, lds, wave0,
;                       [](int g, int) { return g * 16; }, [=](int g, int r, int c, const float* v) { KVR[(size_t)(8192 + r) * 2048 + g * 16 + c] = (bf16)(pk2(v[0], 0.f) & 0xffffu); }); }
.LBB0_419:
	s_cmpk_lt_i32 s11, 0xc0
	v_mbcnt_lo_u32_b32 v4, -1, 0
	v_mbcnt_hi_u32_b32 v4, -1, v4
	s_cbranch_scc1 .LBB0_424
	v_readlane_b32 s0, v253, 16
	v_readlane_b32 s1, v253, 17
	s_lshl_b64 s[20:21], s[0:1], 1
	s_add_u32 s18, s18, s20
	s_addc_u32 s19, s19, s21
	v_readlane_b32 s0, v253, 25
	v_and_b32_e32 v6, 15, v4
	s_add_u32 s20, s16, s20
	v_or_b32_e32 v5, s0, v4
	s_movk_i32 s0, 0x100
	s_addc_u32 s21, s17, s21
	v_lshlrev_b32_e32 v148, 9, v6
	v_cmp_gt_i32_e32 vcc, s0, v5
	s_waitcnt vmcnt(0)
	v_lshl_add_u32 v8, v5, 2, 0
	v_ashrrev_i32_e32 v5, 4, v5
	v_lshl_add_u64 v[0:1], s[20:21], 0, v[148:149]
	v_lshrrev_b32_e32 v9, 1, v4
	v_and_b32_e32 v148, 48, v4
	v_lshlrev_b32_e32 v7, 4, v4
	v_bfi_b32 v4, -4, v5, v4
	v_add_u32_e32 v4, 0x2000, v4
	v_ashrrev_i32_e32 v5, 31, v4
	v_lshlrev_b64 v[4:5], 12, v[4:5]
	v_lshl_add_u64 v[0:1], v[0:1], 0, v[148:149]
	s_mov_b64 s[20:21], 0x20850000
	v_lshl_add_u64 v[2:3], s[18:19], 0, v[148:149]
	v_and_b32_e32 v7, 0x3f0, v7
	v_lshl_add_u64 v[4:5], s[44:45], 0, v[4:5]
	v_and_b32_e32 v148, 30, v9
	v_lshl_add_u64 v[0:1], v[0:1], 0, s[20:21]
	v_add_u32_e32 v7, s87, v7
	v_lshl_add_u64 v[4:5], v[4:5], 0, v[148:149]
	s_add_i32 s7, s11, 0xffffff40
	s_lshl_b32 s22, s7, 4
	s_movk_i32 s5, 0x400
	v_readlane_b32 s1, v253, 26
	s_branch .LBB0_422
.LBB0_421:
	s_or_b64 exec, exec, s[24:25]
	s_addk_i32 s7, 0x40
	s_add_i32 s22, s22, s5
	s_cmpk_gt_i32 s7, 0x7f
	s_barrier
	s_cbranch_scc1 .LBB0_424
